# A/B mirror: static s_setprio 1 for waves 0-3 instead of 4-7 (per-phase flips deleted)
# speedup vs baseline: 1.0134x; 1.0005x over previous
.LBB0_56:
	s_ashr_i32 s37, s36, 31
	v_cmp_lt_i64_e32 vcc, s[40:41], v[150:151]
	s_lshl_b64 s[40:41], s[36:37], 19
	s_add_u32 s40, s52, s40
	s_addc_u32 s41, s53, s41
	s_and_b64 s[44:45], vcc, exec
	s_cselect_b32 s37, s41, s1
	s_cselect_b32 s60, s40, s0
	s_ashr_i32 s35, s34, 31
	s_lshl_b64 s[44:45], s[34:35], 19
	s_add_u32 s44, s19, s44
	s_addc_u32 s45, s24, s45
	s_and_b64 s[48:49], vcc, exec
	s_cselect_b32 s35, s45, s23
	s_cselect_b32 s61, s44, s22
	s_add_u32 s0, s0, 0x40080
	s_addc_u32 s1, s1, 0
	s_add_u32 s62, s22, 0x100
	s_addc_u32 s63, s23, 0
	s_mov_b32 s64, -2
	v_mov_b64_e32 v[82:83], 0
	v_mov_b64_e32 v[84:85], 0
	s_nop 1
	v_mfma_f32_32x32x16_bf16 v[2:17], v[82:85], v[82:85], 0
	v_mov_b64_e32 v[114:115], 0
	v_mov_b64_e32 v[116:117], 0
	v_mov_b64_e32 v[118:119], 0
	v_mov_b64_e32 v[120:121], 0
	v_mov_b64_e32 v[122:123], 0
	v_mfma_f32_32x32x16_bf16 v[18:33], v[82:85], v[82:85], 0
	v_mov_b64_e32 v[124:125], 0
	v_mov_b64_e32 v[126:127], 0
	v_mov_b64_e32 v[128:129], 0
	v_mov_b64_e32 v[98:99], 0
	v_mov_b64_e32 v[100:101], 0
	v_mfma_f32_32x32x16_bf16 v[34:49], v[82:85], v[82:85], 0
	v_mov_b64_e32 v[102:103], 0
	v_mov_b64_e32 v[104:105], 0
	v_mov_b64_e32 v[106:107], 0
	v_mov_b64_e32 v[108:109], 0
	v_mov_b64_e32 v[110:111], 0
	v_mfma_f32_32x32x16_bf16 v[50:65], v[82:85], v[82:85], 0
	v_mov_b64_e32 v[112:113], 0
	v_mov_b64_e32 v[86:87], 0
	v_mov_b64_e32 v[88:89], 0
	v_mov_b64_e32 v[90:91], 0
	v_mov_b64_e32 v[92:93], 0
	v_mfma_f32_32x32x16_bf16 v[66:81], v[82:85], v[82:85], 0
	v_mov_b64_e32 v[94:95], 0
	v_mov_b64_e32 v[96:97], 0
	v_readfirstlane_b32 s98, v204
	s_lshr_b32 s98, s98, 8
	s_cmp_lg_u32 s98, 0
	s_cbranch_scc1 .Lkprio_5
	s_setprio 1

.LBB0_94:
	s_ashr_i32 s49, s48, 31
	s_lshl_b64 s[26:27], s[48:49], 19
	s_add_u32 s50, s14, s26
	v_cmp_lt_i64_e32 vcc, s[28:29], v[152:153]
	s_addc_u32 s51, s15, s27
	s_and_b64 s[26:27], vcc, exec
	s_cselect_b32 s25, s51, s9
	s_cselect_b32 s26, s50, s8
	s_ashr_i32 s47, s46, 31
	s_lshl_b64 s[28:29], s[46:47], 19
	s_add_u32 s54, s19, s28
	s_addc_u32 s55, s34, s29
	s_and_b64 s[28:29], vcc, exec
	s_cselect_b32 s27, s55, s23
	s_cselect_b32 s30, s54, s22
	s_add_u32 s8, s8, 0x40080
	s_addc_u32 s9, s9, 0
	s_add_u32 s31, s22, 0x100
	s_addc_u32 s47, s23, 0
	s_mov_b32 s49, -2
	v_mov_b64_e32 v[50:51], 0
	v_mov_b64_e32 v[52:53], 0
	s_nop 1
	v_mfma_f32_32x32x16_bf16 v[2:17], v[50:53], v[50:53], 0
	v_mov_b64_e32 v[54:55], 0
	v_mov_b64_e32 v[56:57], 0
	v_mov_b64_e32 v[62:63], 0
	v_mov_b64_e32 v[64:65], 0
	v_mov_b64_e32 v[70:71], 0
	v_mfma_f32_32x32x16_bf16 v[18:33], v[50:53], v[50:53], 0
	v_mov_b64_e32 v[72:73], 0
	v_mov_b64_e32 v[130:131], 0
	v_mov_b64_e32 v[132:133], 0
	v_mov_b64_e32 v[134:135], 0
	v_mov_b64_e32 v[136:137], 0
	v_mfma_f32_32x32x16_bf16 v[34:49], v[50:53], v[50:53], 0
	v_mov_b64_e32 v[138:139], 0
	v_mov_b64_e32 v[140:141], 0
	v_mov_b64_e32 v[142:143], 0
	v_mov_b64_e32 v[144:145], 0
	v_mov_b64_e32 v[114:115], 0
	v_mfma_f32_32x32x16_bf16 v[82:97], v[50:53], v[50:53], 0
	v_mov_b64_e32 v[116:117], 0
	v_mov_b64_e32 v[118:119], 0
	v_mov_b64_e32 v[120:121], 0
	v_mov_b64_e32 v[122:123], 0
	v_mov_b64_e32 v[124:125], 0
	v_mfma_f32_32x32x16_bf16 v[98:113], v[50:53], v[50:53], 0
	v_mov_b64_e32 v[126:127], 0
	v_mov_b64_e32 v[128:129], 0
	v_readfirstlane_b32 s98, v204
	s_lshr_b32 s98, s98, 8
	s_cmp_lg_u32 s98, 0
	s_cbranch_scc1 .Lkprio_4
	s_setprio 1

.LBB0_259:
	s_ashr_i32 s35, s34, 31
	v_cmp_lt_i64_e32 vcc, s[36:37], v[150:151]
	s_lshl_b64 s[36:37], s[34:35], 19
	s_add_u32 s36, s12, s36
	s_addc_u32 s37, s13, s37
	s_and_b64 s[42:43], vcc, exec
	s_cselect_b32 s35, s37, s1
	s_cselect_b32 s55, s36, s0
	s_ashr_i32 s31, s30, 31
	s_lshl_b64 s[42:43], s[30:31], 19
	s_add_u32 s42, s17, s42
	s_addc_u32 s43, s19, s43
	s_and_b64 s[46:47], vcc, exec
	s_cselect_b32 s31, s43, s23
	s_cselect_b32 s56, s42, s22
	s_add_u32 s0, s0, 0x40080
	s_addc_u32 s1, s1, 0
	s_add_u32 s57, s22, 0x100
	s_addc_u32 s58, s23, 0
	s_mov_b32 s59, -2
	v_mov_b64_e32 v[82:83], 0
	v_mov_b64_e32 v[84:85], 0
	s_nop 1
	v_mfma_f32_32x32x16_bf16 v[2:17], v[82:85], v[82:85], 0
	v_mov_b64_e32 v[114:115], 0
	v_mov_b64_e32 v[116:117], 0
	v_mov_b64_e32 v[118:119], 0
	v_mov_b64_e32 v[120:121], 0
	v_mov_b64_e32 v[122:123], 0
	v_mfma_f32_32x32x16_bf16 v[18:33], v[82:85], v[82:85], 0
	v_mov_b64_e32 v[124:125], 0
	v_mov_b64_e32 v[126:127], 0
	v_mov_b64_e32 v[128:129], 0
	v_mov_b64_e32 v[98:99], 0
	v_mov_b64_e32 v[100:101], 0
	v_mfma_f32_32x32x16_bf16 v[34:49], v[82:85], v[82:85], 0
	v_mov_b64_e32 v[102:103], 0
	v_mov_b64_e32 v[104:105], 0
	v_mov_b64_e32 v[106:107], 0
	v_mov_b64_e32 v[108:109], 0
	v_mov_b64_e32 v[110:111], 0
	v_mfma_f32_32x32x16_bf16 v[50:65], v[82:85], v[82:85], 0
	v_mov_b64_e32 v[112:113], 0
	v_mov_b64_e32 v[86:87], 0
	v_mov_b64_e32 v[88:89], 0
	v_mov_b64_e32 v[90:91], 0
	v_mov_b64_e32 v[92:93], 0
	v_mfma_f32_32x32x16_bf16 v[66:81], v[82:85], v[82:85], 0
	v_mov_b64_e32 v[94:95], 0
	v_mov_b64_e32 v[96:97], 0
	v_readfirstlane_b32 s98, v204
	s_lshr_b32 s98, s98, 8
	s_cmp_lg_u32 s98, 0
	s_cbranch_scc1 .Lkprio_3
	s_setprio 1

.LBB0_330:
	s_add_u32 s40, s22, 0x100
	s_addc_u32 s41, s23, 0
	s_mov_b32 s51, -2
	v_mov_b64_e32 v[82:83], 0
	v_mov_b64_e32 v[84:85], 0
	s_nop 1
	v_mfma_f32_32x32x16_bf16 v[2:17], v[82:85], v[82:85], 0
	v_mov_b64_e32 v[114:115], 0
	v_mov_b64_e32 v[116:117], 0
	v_mov_b64_e32 v[118:119], 0
	v_mov_b64_e32 v[120:121], 0
	v_mov_b64_e32 v[122:123], 0
	v_mfma_f32_32x32x16_bf16 v[18:33], v[82:85], v[82:85], 0
	v_mov_b64_e32 v[124:125], 0
	v_mov_b64_e32 v[126:127], 0
	v_mov_b64_e32 v[128:129], 0
	v_mov_b64_e32 v[98:99], 0
	v_mov_b64_e32 v[100:101], 0
	v_mfma_f32_32x32x16_bf16 v[34:49], v[82:85], v[82:85], 0
	v_mov_b64_e32 v[102:103], 0
	v_mov_b64_e32 v[104:105], 0
	v_mov_b64_e32 v[106:107], 0
	v_mov_b64_e32 v[108:109], 0
	v_mov_b64_e32 v[110:111], 0
	v_mfma_f32_32x32x16_bf16 v[50:65], v[82:85], v[82:85], 0
	v_mov_b64_e32 v[112:113], 0
	v_mov_b64_e32 v[86:87], 0
	v_mov_b64_e32 v[88:89], 0
	v_mov_b64_e32 v[90:91], 0
	v_mov_b64_e32 v[92:93], 0
	v_mfma_f32_32x32x16_bf16 v[66:81], v[82:85], v[82:85], 0
	v_mov_b64_e32 v[94:95], 0
	v_mov_b64_e32 v[96:97], 0
	v_readfirstlane_b32 s98, v204
	s_lshr_b32 s98, s98, 8
	s_cmp_lg_u32 s98, 0
	s_cbranch_scc1 .Lkprio_2
	s_setprio 1

.LBB0_359:
	s_ashr_i32 s35, s34, 31
	v_cmp_lt_i64_e32 vcc, s[36:37], v[156:157]
	s_lshl_b64 s[36:37], s[34:35], 19
	s_add_u32 s36, s12, s36
	s_addc_u32 s37, s13, s37
	s_and_b64 s[40:41], vcc, exec
	s_cselect_b32 s1, s37, s45
	s_cselect_b32 s3, s36, s44
	s_ashr_i32 s31, s30, 31
	s_lshl_b64 s[40:41], s[30:31], 19
	s_add_u32 s40, s48, s40
	s_addc_u32 s41, s49, s41
	s_and_b64 s[46:47], vcc, exec
	s_cselect_b32 s31, s41, s43
	s_cselect_b32 s35, s40, s42
	s_add_u32 s60, s42, 0x100
	s_addc_u32 s61, s43, 0
	s_add_u32 s42, s44, 0x40080
	s_addc_u32 s43, s45, 0
	s_mov_b32 s62, -2
	v_mov_b64_e32 v[98:99], 0
	v_mov_b64_e32 v[100:101], 0
	s_nop 1
	v_mfma_f32_32x32x16_bf16 v[2:17], v[98:101], v[98:101], 0
	v_mov_b64_e32 v[130:131], 0
	v_mov_b64_e32 v[132:133], 0
	v_mov_b64_e32 v[134:135], 0
	v_mov_b64_e32 v[136:137], 0
	v_mov_b64_e32 v[138:139], 0
	v_mfma_f32_32x32x16_bf16 v[18:33], v[98:101], v[98:101], 0
	v_mov_b64_e32 v[140:141], 0
	v_mov_b64_e32 v[142:143], 0
	v_mov_b64_e32 v[144:145], 0
	v_mov_b64_e32 v[114:115], 0
	v_mov_b64_e32 v[116:117], 0
	v_mfma_f32_32x32x16_bf16 v[34:49], v[98:101], v[98:101], 0
	v_mov_b64_e32 v[118:119], 0
	v_mov_b64_e32 v[120:121], 0
	v_mov_b64_e32 v[122:123], 0
	v_mov_b64_e32 v[124:125], 0
	v_mov_b64_e32 v[126:127], 0
	v_mfma_f32_32x32x16_bf16 v[50:65], v[98:101], v[98:101], 0
	v_mov_b64_e32 v[128:129], 0
	v_mov_b64_e32 v[102:103], 0
	v_mov_b64_e32 v[104:105], 0
	v_mov_b64_e32 v[106:107], 0
	v_mov_b64_e32 v[108:109], 0
	v_mfma_f32_32x32x16_bf16 v[66:81], v[98:101], v[98:101], 0
	v_mov_b64_e32 v[110:111], 0
	v_mov_b64_e32 v[112:113], 0
	v_readfirstlane_b32 s98, v204
	s_lshr_b32 s98, s98, 8
	s_cmp_lg_u32 s98, 0
	s_cbranch_scc1 .Lkprio_1
	s_setprio 1

.LBB0_585:
	s_ashr_i32 s9, s8, 31
	v_cmp_lt_i64_e32 vcc, s[16:17], v[160:161]
	s_lshl_b64 s[16:17], s[8:9], 19
	s_add_u32 s16, s12, s16
	s_addc_u32 s17, s13, s17
	s_and_b64 s[18:19], vcc, exec
	s_cselect_b32 s9, s17, s21
	s_cselect_b32 s43, s16, s20
	s_ashr_i32 s1, s0, 31
	s_lshl_b64 s[18:19], s[0:1], 19
	s_add_u32 s18, s27, s18
	s_addc_u32 s19, s28, s19
	s_and_b64 s[24:25], vcc, exec
	s_cselect_b32 s1, s19, s23
	s_cselect_b32 s44, s18, s22
	s_add_u32 s20, s20, 0x40080
	s_addc_u32 s21, s21, 0
	s_add_u32 s45, s22, 0x100
	s_addc_u32 s46, s23, 0
	s_mov_b32 s47, -2
	v_mov_b64_e32 v[82:83], 0
	v_mov_b64_e32 v[84:85], 0
	s_nop 1
	v_mfma_f32_32x32x16_bf16 v[2:17], v[82:85], v[82:85], 0
	v_mov_b64_e32 v[114:115], 0
	v_mov_b64_e32 v[116:117], 0
	v_mov_b64_e32 v[118:119], 0
	v_mov_b64_e32 v[120:121], 0
	v_mov_b64_e32 v[122:123], 0
	v_mfma_f32_32x32x16_bf16 v[18:33], v[82:85], v[82:85], 0
	v_mov_b64_e32 v[124:125], 0
	v_mov_b64_e32 v[126:127], 0
	v_mov_b64_e32 v[128:129], 0
	v_mov_b64_e32 v[98:99], 0
	v_mov_b64_e32 v[100:101], 0
	v_mfma_f32_32x32x16_bf16 v[34:49], v[82:85], v[82:85], 0
	v_mov_b64_e32 v[102:103], 0
	v_mov_b64_e32 v[104:105], 0
	v_mov_b64_e32 v[106:107], 0
	v_mov_b64_e32 v[108:109], 0
	v_mov_b64_e32 v[110:111], 0
	v_mfma_f32_32x32x16_bf16 v[50:65], v[82:85], v[82:85], 0
	v_mov_b64_e32 v[112:113], 0
	v_mov_b64_e32 v[86:87], 0
	v_mov_b64_e32 v[88:89], 0
	v_mov_b64_e32 v[90:91], 0
	v_mov_b64_e32 v[92:93], 0
	v_mfma_f32_32x32x16_bf16 v[66:81], v[82:85], v[82:85], 0
	v_mov_b64_e32 v[94:95], 0
	v_mov_b64_e32 v[96:97], 0
	v_readfirstlane_b32 s98, v204
	s_lshr_b32 s98, s98, 8
	s_cmp_lg_u32 s98, 0
	s_cbranch_scc1 .Lkprio_0
	s_setprio 1
